# XCD-local grid barrier at seams 1,6,7,8,10,14 (leader skips L2 writeback and cross-XCD arrival when the blockIdx-to-XCC mapping is verified at run time); staddr uses s100/s101
# baseline (speedup 1.0000x reference)
_Z8yoco_fwd4Args:
	s_mov_b32 s99, 1
	s_load_dwordx4 s[20:23], s[0:1], 0xb0
	s_load_dwordx2 s[38:39], s[0:1], 0xc0
	s_load_dword s86, s[0:1], 0xc8
	s_add_u32 s40, s0, 0xc0
	v_and_b32_e32 v1, 0x3ff, v0
	s_addc_u32 s41, s1, 0
	v_readfirstlane_b32 s3, v1
	v_cmp_gt_u32_e32 vcc, 64, v1
	s_and_saveexec_b64 s[4:5], vcc
	v_lshl_add_u32 v2, v1, 2, 0
	v_add_u32_e32 v2, 0x20000, v2
	v_mov_b32_e32 v3, 0
	ds_write_b32 v2, v3
	s_or_b64 exec, exec, s[4:5]
	s_mov_b64 s[4:5], s[0:1]
	s_waitcnt lgkmcnt(0)
	s_barrier
	s_load_dwordx2 s[34:35], s[4:5], 0xa8
	s_getreg_b32 s4, hwreg(HW_REG_XCC_ID, 0, 4)
	v_cmp_eq_u32_e64 s[18:19], 0, v1
	s_waitcnt lgkmcnt(0)
	s_add_u32 s36, s34, 0x300000
	s_addc_u32 s37, s35, 0
	s_and_b32 s33, s4, 15
	s_and_saveexec_b64 s[4:5], s[18:19]
	s_cbranch_execz .LBB0_5
	s_mov_b64 s[6:7], exec
	v_mbcnt_lo_u32_b32 v2, s6, 0
	v_mbcnt_hi_u32_b32 v2, s7, v2
	v_cmp_eq_u32_e32 vcc, 0, v2
	s_and_b64 s[8:9], exec, vcc
	s_mov_b64 exec, s[8:9]
	s_cbranch_execz .LBB0_5
	s_lshl_b32 s8, s33, 8
	s_bcnt1_i32_b64 s6, s[6:7]
	v_mov_b32_e32 v2, s8
	v_mov_b32_e32 v3, s6
	global_atomic_add v2, v3, s[36:37] offset:1024
	s_and_b32 s8, s2, 7
	s_xor_b32 s8, s8, s33
	s_and_b32 s6, s38, 7
	s_or_b32 s8, s8, s6
	s_cmp_eq_u32 s8, 0
	s_cbranch_scc1 .Lxl_pure
	v_mov_b32_e32 v2, 0x3700
	v_mov_b32_e32 v3, 1
	global_atomic_add v2, v3, s[36:37]
.Lxl_pure:
.LBB0_5:
	s_or_b64 exec, exec, s[4:5]
	s_lshr_b32 s3, s3, 6
	s_lshl_b32 s4, s2, 3
	s_add_i32 s28, s3, s4
	s_lshl_b32 s30, s38, 3
	s_cmp_lt_i32 s20, 1
	s_cselect_b64 s[4:5], -1, 0
	s_cmp_gt_i32 s21, 0
	s_cselect_b64 s[6:7], -1, 0
	s_and_b64 s[12:13], s[4:5], s[6:7]
	s_andn2_b64 vcc, exec, s[12:13]
	v_and_b32_e32 v242, 63, v1
	s_cbranch_vccnz .LBB0_74
	v_lshlrev_b32_e32 v2, 2, v1
	s_lshl_b32 s4, s2, 6
	s_lshl_b32 s5, s3, 3
	v_and_b32_e32 v83, 0x7c, v2
	v_lshrrev_b32_e32 v2, 2, v1
	s_add_i32 s4, s4, s5
	s_lshl_b32 s23, s2, 10
	s_lshl_b32 s3, s3, 7
	v_and_b32_e32 v82, 8, v2
	v_mov_b32_e32 v85, 0
	s_add_i32 s29, s4, 0x7ea00
	s_lshl_b32 s31, s38, 6
	s_add_i32 s42, s23, s3
	s_lshl_b32 s3, s38, 10
	s_mov_b32 s43, 0x100000
	s_movk_i32 s44, 0x3000
	s_mov_b32 s9, 0
	s_movk_i32 s45, 0x6000
	s_mov_b32 s46, 0x9000
	s_mov_b32 s47, 0xc000
	s_mov_b32 s48, 0x15000
	s_mov_b32 s49, 0x33000
	s_mov_b64 s[6:7], 0x4600000
	s_movk_i32 s50, 0x7fff
	s_mov_b32 s51, 0xffff0000
	s_mov_b32 s52, 0x4601000
	s_mov_b32 s53, 0x63000
	s_mov_b32 s54, 0x66000
	s_mov_b32 s55, 0x69000
	s_mov_b32 s56, 0x6c000
	s_movk_i32 s57, 0x1000
	s_mov_b64 s[14:15], 0x3000000
	s_movk_i32 s58, 0x2000
	s_movk_i32 s59, 0x4000
	s_movk_i32 s60, 0x7000
	s_mov_b32 s61, 0x11000
	s_mov_b32 s62, 0x13000
	s_mov_b32 s63, 0x17000
	s_mov_b32 s64, 0x3000000
	s_mov_b32 s65, 0x3001000
	s_mov_b32 s66, 0x3002000
	s_mov_b32 s67, 0x3004000
	s_mov_b32 s68, 0x21000
	s_mov_b32 s69, 0x23000
	s_mov_b32 s70, 0x25000
	s_mov_b32 s71, 0x27000
	s_mov_b32 s72, 0x31000
	s_mov_b32 s73, 0x35000
	s_mov_b32 s74, 0x37000
	s_mov_b64 s[16:17], 0x400000
	s_movk_i32 s75, 0x5800
	v_mov_b32_e32 v100, 1
	s_mov_b32 s76, s28
	s_branch .LBB0_8

.LBB0_140:
	s_or_b64 exec, exec, s[6:7]
	s_waitcnt lgkmcnt(0)
	s_barrier
	v_mov_b32_e32 v2, 0x3700
	global_load_dword v2, v2, s[36:37] sc1
	s_waitcnt vmcnt(0)
	v_readfirstlane_b32 s99, v2

.Lz_post_p1:
	s_lshl_b32 s25, s46, 8
	v_add_u32_e32 v148, s25, v150
	v_ashrrev_i32_e32 v149, 31, v148
	v_lshl_add_u64 v[244:245], v[148:149], 2, s[8:9]
	global_load_dword v149, v[244:245], off
	global_load_dword v232, v[244:245], off offset:64
	global_load_dword v233, v[244:245], off offset:128
	global_load_dword v234, v[244:245], off offset:192
	global_load_dword v235, v[244:245], off offset:512
	global_load_dword v236, v[244:245], off offset:576
	global_load_dword v237, v[244:245], off offset:640
	global_load_dword v238, v[244:245], off offset:704
	v_pk_mul_f32 v[128:129], v[120:121], v[128:129]
	v_pk_mul_f32 v[126:127], v[118:119], v[126:127]
	v_pk_mul_f32 v[124:125], v[116:117], v[124:125]
	v_pk_mul_f32 v[244:245], v[114:115], v[122:123]
	s_lshl_b32 s46, s47, 7
	v_mov_b64_e32 v[122:123], s[12:13]
	s_ashr_i32 s47, s46, 31
	v_mad_i64_i32 v[248:249], s[48:49], v148, s68, v[122:123]
	s_lshl_b64 s[46:47], s[46:47], 1
	v_lshl_add_u64 v[248:249], v[248:249], 0, s[46:47]
	v_lshl_add_u64 v[248:249], v[248:249], 0, v[138:139]
	v_mov_b64_e32 v[240:241], v[248:249]
	s_mov_b32 s101, 0
	v_pk_mul_f32 v[112:113], v[108:109], v[112:113]
	v_pk_mul_f32 v[110:111], v[106:107], v[110:111]
	v_pk_mul_f32 v[104:105], v[100:101], v[104:105]
	v_pk_mul_f32 v[102:103], v[98:99], v[102:103]
	v_pk_mul_f32 v[96:97], v[92:93], v[96:97]
	v_pk_mul_f32 v[94:95], v[90:91], v[94:95]
	v_pk_mul_f32 v[88:89], v[84:85], v[88:89]
	v_pk_mul_f32 v[86:87], v[82:83], v[86:87]
	v_pk_mul_f32 v[80:81], v[76:77], v[80:81]
	v_pk_mul_f32 v[78:79], v[74:75], v[78:79]
	v_pk_mul_f32 v[72:73], v[68:69], v[72:73]
	v_pk_mul_f32 v[70:71], v[66:67], v[70:71]
	v_pk_mul_f32 v[64:65], v[60:61], v[64:65]
	v_pk_mul_f32 v[62:63], v[58:59], v[62:63]
	v_pk_mul_f32 v[56:57], v[52:53], v[56:57]
	v_pk_mul_f32 v[54:55], v[50:51], v[54:55]
	v_pk_mul_f32 v[48:49], v[44:45], v[48:49]
	v_pk_mul_f32 v[46:47], v[42:43], v[46:47]
	v_pk_mul_f32 v[40:41], v[36:37], v[40:41]
	v_pk_mul_f32 v[38:39], v[34:35], v[38:39]
	v_pk_mul_f32 v[32:33], v[28:29], v[32:33]
	v_pk_mul_f32 v[30:31], v[26:27], v[30:31]
	v_pk_mul_f32 v[24:25], v[20:21], v[24:25]
	v_pk_mul_f32 v[22:23], v[18:19], v[22:23]
	v_pk_mul_f32 v[16:17], v[12:13], v[16:17]
	v_pk_mul_f32 v[14:15], v[10:11], v[14:15]
	v_pk_mul_f32 v[4:5], v[8:9], v[4:5]
	v_pk_mul_f32 v[2:3], v[6:7], v[2:3]
	s_and_b64 vcc, exec, s[16:17]
	s_cbranch_vccz .LBB0_155
	s_barrier
.LBB0_155:
	ds_read_b128 v[160:163], v155
	ds_read_b128 v[164:167], v155 offset:1024
	ds_read_b128 v[168:171], v155 offset:2048
	ds_read_b128 v[172:175], v155 offset:3072
	ds_read_b128 v[176:179], v156
	ds_read_b128 v[180:183], v156 offset:1024
	ds_read_b128 v[184:187], v156 offset:2048
	ds_read_b128 v[188:191], v156 offset:3072
	ds_read_b128 v[192:195], v157
	ds_read_b128 v[196:199], v157 offset:1024
	ds_read_b128 v[200:203], v157 offset:2048
	ds_read_b128 v[204:207], v157 offset:3072
	ds_read_b128 v[208:211], v157 offset:4096
	ds_read_b128 v[212:215], v157 offset:5120
	ds_read_b128 v[216:219], v157 offset:6144
	ds_read_b128 v[220:223], v157 offset:7168
	s_andn2_b64 vcc, exec, s[4:5]
	s_waitcnt vmcnt(0)
	v_fmamk_f32 v239, v149, 0x3a800000, v158
	v_rsq_f32_e32 v149, v239
	s_nop 0
	v_mul_f32_e32 v252, 0xbfb8aa3b, v149
	v_pk_mul_f32 v[120:121], v[120:121], v[252:253] op_sel_hi:[1,0]
	v_pk_mul_f32 v[118:119], v[118:119], v[252:253] op_sel_hi:[1,0]
	v_pk_mul_f32 v[116:117], v[116:117], v[252:253] op_sel_hi:[1,0]
	v_pk_mul_f32 v[114:115], v[114:115], v[252:253] op_sel_hi:[1,0]
	v_exp_f32_e32 v118, v118
	v_exp_f32_e32 v119, v119
	v_exp_f32_e32 v120, v120
	v_exp_f32_e32 v121, v121
	v_exp_f32_e32 v114, v114
	v_exp_f32_e32 v115, v115
	v_exp_f32_e32 v116, v116
	v_exp_f32_e32 v117, v117
	v_fma_f32 v118, v118, v239, v239
	v_fma_f32 v119, v119, v239, v239
	v_fma_f32 v120, v120, v239, v239
	v_fma_f32 v121, v121, v239, v239
	v_fma_f32 v149, v114, v239, v239
	v_fma_f32 v159, v115, v239, v239
	v_fma_f32 v247, v116, v239, v239
	v_fma_f32 v252, v117, v239, v239
	v_rcp_f32_e32 v114, v118
	v_rcp_f32_e32 v115, v119
	v_rcp_f32_e32 v116, v120
	v_rcp_f32_e32 v117, v121
	v_rcp_f32_e32 v118, v149
	v_rcp_f32_e32 v119, v159
	v_rcp_f32_e32 v120, v247
	v_rcp_f32_e32 v121, v252
	v_pk_mul_f32 v[116:117], v[128:129], v[116:117]
	v_pk_mul_f32 v[114:115], v[126:127], v[114:115]
	v_pk_mul_f32 v[120:121], v[124:125], v[120:121]
	v_pk_mul_f32 v[118:119], v[244:245], v[118:119]
	v_cvt_pk_bf16_f32 v114, v114, v115
	v_cvt_pk_bf16_f32 v115, v116, v117
	v_cvt_pk_bf16_f32 v116, v118, v119
	v_cvt_pk_bf16_f32 v117, v120, v121
	global_store_dwordx4 v[248:249], v[114:117], off
	v_fmamk_f32 v239, v232, 0x3a800000, v158
	v_rsq_f32_e32 v121, v239
	s_nop 0
	v_mul_f32_e32 v120, 0xbfb8aa3b, v121
	v_pk_mul_f32 v[108:109], v[108:109], v[120:121] op_sel_hi:[1,0]
	v_pk_mul_f32 v[106:107], v[106:107], v[120:121] op_sel_hi:[1,0]
	v_pk_mul_f32 v[100:101], v[100:101], v[120:121] op_sel_hi:[1,0]
	v_pk_mul_f32 v[98:99], v[98:99], v[120:121] op_sel_hi:[1,0]
	v_exp_f32_e32 v106, v106
	v_exp_f32_e32 v107, v107
	v_exp_f32_e32 v108, v108
	v_exp_f32_e32 v109, v109
	v_exp_f32_e32 v98, v98
	v_exp_f32_e32 v99, v99
	v_exp_f32_e32 v100, v100
	v_exp_f32_e32 v101, v101
	v_fma_f32 v106, v106, v239, v239
	v_fma_f32 v107, v107, v239, v239
	v_fma_f32 v108, v108, v239, v239
	v_fma_f32 v109, v109, v239, v239
	v_fma_f32 v115, v98, v239, v239
	v_fma_f32 v120, v99, v239, v239
	v_fma_f32 v121, v100, v239, v239
	v_fma_f32 v125, v101, v239, v239
	v_rcp_f32_e32 v98, v106
	v_rcp_f32_e32 v99, v107
	v_rcp_f32_e32 v100, v108
	v_rcp_f32_e32 v101, v109
	v_rcp_f32_e32 v106, v115
	v_rcp_f32_e32 v107, v120
	v_rcp_f32_e32 v108, v121
	v_rcp_f32_e32 v109, v125
	v_pk_mul_f32 v[100:101], v[112:113], v[100:101]
	v_pk_mul_f32 v[98:99], v[110:111], v[98:99]
	v_pk_mul_f32 v[104:105], v[104:105], v[108:109]
	v_pk_mul_f32 v[102:103], v[102:103], v[106:107]
	s_mov_b32 s100, 0x16000
	v_lshl_add_u64 v[116:117], v[240:241], 0, s[100:101]
	v_cvt_pk_bf16_f32 v98, v98, v99
	v_cvt_pk_bf16_f32 v99, v100, v101
	v_cvt_pk_bf16_f32 v100, v102, v103
	v_cvt_pk_bf16_f32 v101, v104, v105
	global_store_dwordx4 v[116:117], v[98:101], off
	v_fmamk_f32 v239, v233, 0x3a800000, v158
	v_rsq_f32_e32 v105, v239
	s_nop 0
	v_mul_f32_e32 v104, 0xbfb8aa3b, v105
	v_pk_mul_f32 v[92:93], v[92:93], v[104:105] op_sel_hi:[1,0]
	v_pk_mul_f32 v[90:91], v[90:91], v[104:105] op_sel_hi:[1,0]
	v_pk_mul_f32 v[84:85], v[84:85], v[104:105] op_sel_hi:[1,0]
	v_pk_mul_f32 v[82:83], v[82:83], v[104:105] op_sel_hi:[1,0]
	v_exp_f32_e32 v90, v90
	v_exp_f32_e32 v91, v91
	v_exp_f32_e32 v92, v92
	v_exp_f32_e32 v93, v93
	v_exp_f32_e32 v82, v82
	v_exp_f32_e32 v83, v83
	v_exp_f32_e32 v84, v84
	v_exp_f32_e32 v85, v85
	v_fma_f32 v90, v90, v239, v239
	v_fma_f32 v91, v91, v239, v239
	v_fma_f32 v92, v92, v239, v239
	v_fma_f32 v93, v93, v239, v239
	v_fma_f32 v99, v82, v239, v239
	v_fma_f32 v104, v83, v239, v239
	v_fma_f32 v105, v84, v239, v239
	v_fma_f32 v107, v85, v239, v239
	v_rcp_f32_e32 v82, v90
	v_rcp_f32_e32 v83, v91
	v_rcp_f32_e32 v84, v92
	v_rcp_f32_e32 v85, v93
	v_rcp_f32_e32 v90, v99
	v_rcp_f32_e32 v91, v104
	v_rcp_f32_e32 v92, v105
	v_rcp_f32_e32 v93, v107
	v_pk_mul_f32 v[84:85], v[96:97], v[84:85]
	v_pk_mul_f32 v[82:83], v[94:95], v[82:83]
	v_pk_mul_f32 v[88:89], v[88:89], v[92:93]
	v_pk_mul_f32 v[86:87], v[86:87], v[90:91]
	s_mov_b32 s100, 0x2c000
	v_lshl_add_u64 v[100:101], v[240:241], 0, s[100:101]
	v_cvt_pk_bf16_f32 v82, v82, v83
	v_cvt_pk_bf16_f32 v83, v84, v85
	v_cvt_pk_bf16_f32 v84, v86, v87
	v_cvt_pk_bf16_f32 v85, v88, v89
	global_store_dwordx4 v[100:101], v[82:85], off
	s_nop 0
	s_nop 0
	s_mov_b32 s100, 0x42000
	v_lshl_add_u64 v[82:83], v[240:241], 0, s[100:101]
	v_fmamk_f32 v239, v234, 0x3a800000, v158
	v_rsq_f32_e32 v89, v239
	s_nop 0
	v_mul_f32_e32 v88, 0xbfb8aa3b, v89
	v_pk_mul_f32 v[76:77], v[76:77], v[88:89] op_sel_hi:[1,0]
	v_pk_mul_f32 v[74:75], v[74:75], v[88:89] op_sel_hi:[1,0]
	v_pk_mul_f32 v[68:69], v[68:69], v[88:89] op_sel_hi:[1,0]
	v_pk_mul_f32 v[66:67], v[66:67], v[88:89] op_sel_hi:[1,0]
	v_exp_f32_e32 v74, v74
	v_exp_f32_e32 v75, v75
	v_exp_f32_e32 v76, v76
	v_exp_f32_e32 v77, v77
	v_exp_f32_e32 v66, v66
	v_exp_f32_e32 v67, v67
	v_exp_f32_e32 v68, v68
	v_exp_f32_e32 v69, v69
	v_fma_f32 v74, v74, v239, v239
	v_fma_f32 v75, v75, v239, v239
	v_fma_f32 v76, v76, v239, v239
	v_fma_f32 v77, v77, v239, v239
	v_fma_f32 v85, v66, v239, v239
	v_fma_f32 v88, v67, v239, v239
	v_fma_f32 v89, v68, v239, v239
	v_fma_f32 v91, v69, v239, v239
	v_rcp_f32_e32 v66, v74
	v_rcp_f32_e32 v67, v75
	v_rcp_f32_e32 v68, v76
	v_rcp_f32_e32 v69, v77
	v_rcp_f32_e32 v74, v85
	v_rcp_f32_e32 v75, v88
	v_rcp_f32_e32 v76, v89
	v_rcp_f32_e32 v77, v91
	v_pk_mul_f32 v[68:69], v[80:81], v[68:69]
	v_pk_mul_f32 v[66:67], v[78:79], v[66:67]
	v_pk_mul_f32 v[72:73], v[72:73], v[76:77]
	v_pk_mul_f32 v[70:71], v[70:71], v[74:75]
	v_cvt_pk_bf16_f32 v66, v66, v67
	v_cvt_pk_bf16_f32 v67, v68, v69
	v_cvt_pk_bf16_f32 v68, v70, v71
	v_cvt_pk_bf16_f32 v69, v72, v73
	global_store_dwordx4 v[82:83], v[66:69], off
	v_fmamk_f32 v239, v235, 0x3a800000, v158
	v_rsq_f32_e32 v73, v239
	s_nop 0
	v_mul_f32_e32 v72, 0xbfb8aa3b, v73
	v_pk_mul_f32 v[60:61], v[60:61], v[72:73] op_sel_hi:[1,0]
	v_pk_mul_f32 v[58:59], v[58:59], v[72:73] op_sel_hi:[1,0]
	v_pk_mul_f32 v[52:53], v[52:53], v[72:73] op_sel_hi:[1,0]
	v_pk_mul_f32 v[50:51], v[50:51], v[72:73] op_sel_hi:[1,0]
	v_exp_f32_e32 v58, v58
	v_exp_f32_e32 v59, v59
	v_exp_f32_e32 v60, v60
	v_exp_f32_e32 v61, v61
	v_exp_f32_e32 v50, v50
	v_exp_f32_e32 v51, v51
	v_exp_f32_e32 v52, v52
	v_exp_f32_e32 v53, v53
	v_fma_f32 v58, v58, v239, v239
	v_fma_f32 v59, v59, v239, v239
	v_fma_f32 v60, v60, v239, v239
	v_fma_f32 v61, v61, v239, v239
	v_fma_f32 v67, v50, v239, v239
	v_fma_f32 v72, v51, v239, v239
	v_fma_f32 v73, v52, v239, v239
	v_fma_f32 v75, v53, v239, v239
	v_rcp_f32_e32 v50, v58
	v_rcp_f32_e32 v51, v59
	v_rcp_f32_e32 v52, v60
	v_rcp_f32_e32 v53, v61
	v_rcp_f32_e32 v58, v67
	v_rcp_f32_e32 v59, v72
	v_rcp_f32_e32 v60, v73
	v_rcp_f32_e32 v61, v75
	v_pk_mul_f32 v[52:53], v[64:65], v[52:53]
	v_pk_mul_f32 v[50:51], v[62:63], v[50:51]
	v_pk_mul_f32 v[56:57], v[56:57], v[60:61]
	v_pk_mul_f32 v[54:55], v[54:55], v[58:59]
	s_mov_b32 s100, 0xb0000
	v_lshl_add_u64 v[68:69], v[240:241], 0, s[100:101]
	v_cvt_pk_bf16_f32 v50, v50, v51
	v_cvt_pk_bf16_f32 v51, v52, v53
	v_cvt_pk_bf16_f32 v52, v54, v55
	v_cvt_pk_bf16_f32 v53, v56, v57
	global_store_dwordx4 v[68:69], v[50:53], off
	v_fmamk_f32 v239, v236, 0x3a800000, v158
	v_rsq_f32_e32 v57, v239
	s_nop 0
	v_mul_f32_e32 v56, 0xbfb8aa3b, v57
	v_pk_mul_f32 v[44:45], v[44:45], v[56:57] op_sel_hi:[1,0]
	v_pk_mul_f32 v[42:43], v[42:43], v[56:57] op_sel_hi:[1,0]
	v_pk_mul_f32 v[36:37], v[36:37], v[56:57] op_sel_hi:[1,0]
	v_pk_mul_f32 v[34:35], v[34:35], v[56:57] op_sel_hi:[1,0]
	v_exp_f32_e32 v42, v42
	v_exp_f32_e32 v43, v43
	v_exp_f32_e32 v44, v44
	v_exp_f32_e32 v45, v45
	v_exp_f32_e32 v34, v34
	v_exp_f32_e32 v35, v35
	v_exp_f32_e32 v36, v36
	v_exp_f32_e32 v37, v37
	v_fma_f32 v42, v42, v239, v239
	v_fma_f32 v43, v43, v239, v239
	v_fma_f32 v44, v44, v239, v239
	v_fma_f32 v45, v45, v239, v239
	v_fma_f32 v51, v34, v239, v239
	v_fma_f32 v56, v35, v239, v239
	v_fma_f32 v57, v36, v239, v239
	v_fma_f32 v59, v37, v239, v239
	v_rcp_f32_e32 v34, v42
	v_rcp_f32_e32 v35, v43
	v_rcp_f32_e32 v36, v44
	v_rcp_f32_e32 v37, v45
	v_rcp_f32_e32 v42, v51
	v_rcp_f32_e32 v43, v56
	v_rcp_f32_e32 v44, v57
	v_rcp_f32_e32 v45, v59
	v_pk_mul_f32 v[36:37], v[48:49], v[36:37]
	v_pk_mul_f32 v[34:35], v[46:47], v[34:35]
	v_pk_mul_f32 v[40:41], v[40:41], v[44:45]
	v_pk_mul_f32 v[38:39], v[38:39], v[42:43]
	s_mov_b32 s100, 0xc6000
	v_lshl_add_u64 v[52:53], v[240:241], 0, s[100:101]
	v_cvt_pk_bf16_f32 v34, v34, v35
	v_cvt_pk_bf16_f32 v35, v36, v37
	v_cvt_pk_bf16_f32 v36, v38, v39
	v_cvt_pk_bf16_f32 v37, v40, v41
	global_store_dwordx4 v[52:53], v[34:37], off
	v_fmamk_f32 v239, v237, 0x3a800000, v158
	v_rsq_f32_e32 v41, v239
	s_nop 0
	v_mul_f32_e32 v40, 0xbfb8aa3b, v41
	v_pk_mul_f32 v[28:29], v[28:29], v[40:41] op_sel_hi:[1,0]
	v_pk_mul_f32 v[26:27], v[26:27], v[40:41] op_sel_hi:[1,0]
	v_pk_mul_f32 v[20:21], v[20:21], v[40:41] op_sel_hi:[1,0]
	v_pk_mul_f32 v[18:19], v[18:19], v[40:41] op_sel_hi:[1,0]
	v_exp_f32_e32 v26, v26
	v_exp_f32_e32 v27, v27
	v_exp_f32_e32 v28, v28
	v_exp_f32_e32 v29, v29
	v_exp_f32_e32 v18, v18
	v_exp_f32_e32 v19, v19
	v_exp_f32_e32 v20, v20
	v_exp_f32_e32 v21, v21
	v_fma_f32 v26, v26, v239, v239
	v_fma_f32 v27, v27, v239, v239
	v_fma_f32 v28, v28, v239, v239
	v_fma_f32 v29, v29, v239, v239
	v_fma_f32 v35, v18, v239, v239
	v_fma_f32 v40, v19, v239, v239
	v_fma_f32 v41, v20, v239, v239
	v_fma_f32 v43, v21, v239, v239
	v_rcp_f32_e32 v18, v26
	v_rcp_f32_e32 v19, v27
	v_rcp_f32_e32 v20, v28
	v_rcp_f32_e32 v21, v29
	v_rcp_f32_e32 v26, v35
	v_rcp_f32_e32 v27, v40
	v_rcp_f32_e32 v28, v41
	v_rcp_f32_e32 v29, v43
	v_pk_mul_f32 v[20:21], v[32:33], v[20:21]
	v_pk_mul_f32 v[18:19], v[30:31], v[18:19]
	v_pk_mul_f32 v[24:25], v[24:25], v[28:29]
	v_pk_mul_f32 v[22:23], v[22:23], v[26:27]
	s_mov_b32 s100, 0xdc000
	v_lshl_add_u64 v[36:37], v[240:241], 0, s[100:101]
	v_cvt_pk_bf16_f32 v18, v18, v19
	v_cvt_pk_bf16_f32 v19, v20, v21
	v_cvt_pk_bf16_f32 v20, v22, v23
	v_cvt_pk_bf16_f32 v21, v24, v25
	global_store_dwordx4 v[36:37], v[18:21], off
	s_nop 0
	s_nop 0
	v_fmamk_f32 v239, v238, 0x3a800000, v158
	v_rsq_f32_e32 v21, v239
	s_nop 0
	v_mul_f32_e32 v20, 0xbfb8aa3b, v21
	v_pk_mul_f32 v[12:13], v[12:13], v[20:21] op_sel_hi:[1,0]
	v_pk_mul_f32 v[10:11], v[10:11], v[20:21] op_sel_hi:[1,0]
	v_pk_mul_f32 v[8:9], v[8:9], v[20:21] op_sel_hi:[1,0]
	v_pk_mul_f32 v[6:7], v[6:7], v[20:21] op_sel_hi:[1,0]
	v_exp_f32_e32 v10, v10
	v_exp_f32_e32 v11, v11
	v_exp_f32_e32 v12, v12
	v_exp_f32_e32 v13, v13
	v_exp_f32_e32 v6, v6
	v_exp_f32_e32 v7, v7
	v_exp_f32_e32 v8, v8
	v_exp_f32_e32 v9, v9
	v_fma_f32 v10, v10, v239, v239
	v_fma_f32 v11, v11, v239, v239
	v_fma_f32 v12, v12, v239, v239
	v_fma_f32 v13, v13, v239, v239
	v_fma_f32 v20, v6, v239, v239
	v_fma_f32 v21, v7, v239, v239
	v_fma_f32 v23, v8, v239, v239
	v_fma_f32 v24, v9, v239, v239
	v_rcp_f32_e32 v6, v10
	v_rcp_f32_e32 v7, v11
	v_rcp_f32_e32 v8, v12
	v_rcp_f32_e32 v9, v13
	v_rcp_f32_e32 v10, v20
	v_rcp_f32_e32 v11, v21
	v_rcp_f32_e32 v12, v23
	v_rcp_f32_e32 v13, v24
	v_pk_mul_f32 v[8:9], v[16:17], v[8:9]
	v_pk_mul_f32 v[6:7], v[14:15], v[6:7]
	v_pk_mul_f32 v[12:13], v[4:5], v[12:13]
	v_pk_mul_f32 v[4:5], v[2:3], v[10:11]
	s_mov_b32 s100, 0xf2000
	v_lshl_add_u64 v[18:19], v[240:241], 0, s[100:101]
	v_cvt_pk_bf16_f32 v2, v6, v7
	v_cvt_pk_bf16_f32 v3, v8, v9
	v_cvt_pk_bf16_f32 v4, v4, v5
	v_cvt_pk_bf16_f32 v5, v12, v13
	s_mov_b64 s[4:5], -1
	global_store_dwordx4 v[18:19], v[2:5], off
	s_cbranch_vccnz .LBB0_148
	s_andn2_b64 vcc, exec, s[10:11]
	s_cbranch_vccnz .LBB0_147
	s_barrier
	s_branch .LBB0_147

.LBB0_205:
	s_andn2_saveexec_b64 s[10:11], s[10:11]
	s_cbranch_execz .LBB0_225
	s_waitcnt lgkmcnt(0)
	s_cmp_eq_u32 s99, 0
	s_cbranch_scc1 .Lxl_1
	s_mov_b64 s[10:11], exec
	buffer_wbl2 sc1
	s_waitcnt lgkmcnt(0)
	s_waitcnt vmcnt(0)
	v_mbcnt_lo_u32_b32 v3, s10, 0
	v_mbcnt_hi_u32_b32 v3, s11, v3
	v_cmp_eq_u32_e32 vcc, 0, v3
	s_and_saveexec_b64 s[12:13], vcc
	s_cbranch_execz .LBB0_208
	s_bcnt1_i32_b64 s3, s[10:11]
	v_mov_b32_e32 v4, 0x303000
	v_mov_b32_e32 v5, s3
	global_atomic_add v4, v4, v5, s[34:35] offset:1024 sc0

.Lxl_1:
	s_mov_b64 s[10:11], exec
	v_mbcnt_lo_u32_b32 v2, s10, 0
	v_mbcnt_hi_u32_b32 v2, s11, v2
	v_cmp_eq_u32_e32 vcc, 0, v2
	s_waitcnt vmcnt(0)
	buffer_inv sc1
	s_and_saveexec_b64 s[12:13], vcc
	s_cbranch_execz .LBB0_224
	s_bcnt1_i32_b64 s3, s[10:11]
	v_mov_b32_e32 v2, 0x2000
	v_mov_b32_e32 v3, s3
	global_atomic_add v2, v3, s[8:9] offset:1024

.Lz_post_p6:
	s_lshl_b32 s25, s46, 8
	v_add_u32_e32 v148, s25, v150
	v_ashrrev_i32_e32 v149, 31, v148
	v_lshl_add_u64 v[244:245], v[148:149], 2, s[10:11]
	global_load_dword v149, v[244:245], off
	global_load_dword v232, v[244:245], off offset:64
	global_load_dword v233, v[244:245], off offset:128
	global_load_dword v234, v[244:245], off offset:192
	global_load_dword v235, v[244:245], off offset:512
	global_load_dword v236, v[244:245], off offset:576
	global_load_dword v237, v[244:245], off offset:640
	global_load_dword v238, v[244:245], off offset:704
	v_pk_mul_f32 v[128:129], v[120:121], v[128:129]
	v_pk_mul_f32 v[126:127], v[118:119], v[126:127]
	v_pk_mul_f32 v[124:125], v[116:117], v[124:125]
	v_pk_mul_f32 v[244:245], v[114:115], v[122:123]
	s_lshl_b32 s46, s47, 7
	v_mov_b64_e32 v[122:123], s[12:13]
	s_ashr_i32 s47, s46, 31
	v_mad_i64_i32 v[248:249], s[48:49], v148, s68, v[122:123]
	s_lshl_b64 s[46:47], s[46:47], 1
	v_lshl_add_u64 v[248:249], v[248:249], 0, s[46:47]
	v_lshl_add_u64 v[248:249], v[248:249], 0, v[138:139]
	v_mov_b64_e32 v[240:241], v[248:249]
	s_mov_b32 s101, 0
	v_pk_mul_f32 v[112:113], v[108:109], v[112:113]
	v_pk_mul_f32 v[110:111], v[106:107], v[110:111]
	v_pk_mul_f32 v[104:105], v[100:101], v[104:105]
	v_pk_mul_f32 v[102:103], v[98:99], v[102:103]
	v_pk_mul_f32 v[96:97], v[92:93], v[96:97]
	v_pk_mul_f32 v[94:95], v[90:91], v[94:95]
	v_pk_mul_f32 v[88:89], v[84:85], v[88:89]
	v_pk_mul_f32 v[86:87], v[82:83], v[86:87]
	v_pk_mul_f32 v[80:81], v[76:77], v[80:81]
	v_pk_mul_f32 v[78:79], v[74:75], v[78:79]
	v_pk_mul_f32 v[72:73], v[68:69], v[72:73]
	v_pk_mul_f32 v[70:71], v[66:67], v[70:71]
	v_pk_mul_f32 v[64:65], v[60:61], v[64:65]
	v_pk_mul_f32 v[62:63], v[58:59], v[62:63]
	v_pk_mul_f32 v[56:57], v[52:53], v[56:57]
	v_pk_mul_f32 v[54:55], v[50:51], v[54:55]
	v_pk_mul_f32 v[48:49], v[44:45], v[48:49]
	v_pk_mul_f32 v[46:47], v[42:43], v[46:47]
	v_pk_mul_f32 v[40:41], v[36:37], v[40:41]
	v_pk_mul_f32 v[38:39], v[34:35], v[38:39]
	v_pk_mul_f32 v[32:33], v[28:29], v[32:33]
	v_pk_mul_f32 v[30:31], v[26:27], v[30:31]
	v_pk_mul_f32 v[24:25], v[20:21], v[24:25]
	v_pk_mul_f32 v[22:23], v[18:19], v[22:23]
	v_pk_mul_f32 v[16:17], v[12:13], v[16:17]
	v_pk_mul_f32 v[14:15], v[10:11], v[14:15]
	v_pk_mul_f32 v[4:5], v[8:9], v[4:5]
	v_pk_mul_f32 v[2:3], v[6:7], v[2:3]
	s_and_b64 vcc, exec, s[16:17]
	s_cbranch_vccz .LBB0_843
	s_barrier
.LBB0_843:
	ds_read_b128 v[160:163], v155
	ds_read_b128 v[164:167], v155 offset:1024
	ds_read_b128 v[168:171], v155 offset:2048
	ds_read_b128 v[172:175], v155 offset:3072
	ds_read_b128 v[176:179], v156
	ds_read_b128 v[180:183], v156 offset:1024
	ds_read_b128 v[184:187], v156 offset:2048
	ds_read_b128 v[188:191], v156 offset:3072
	ds_read_b128 v[192:195], v157
	ds_read_b128 v[196:199], v157 offset:1024
	ds_read_b128 v[200:203], v157 offset:2048
	ds_read_b128 v[204:207], v157 offset:3072
	ds_read_b128 v[208:211], v157 offset:4096
	ds_read_b128 v[212:215], v157 offset:5120
	ds_read_b128 v[216:219], v157 offset:6144
	ds_read_b128 v[220:223], v157 offset:7168
	s_andn2_b64 vcc, exec, s[4:5]
	s_waitcnt vmcnt(0)
	v_fmamk_f32 v239, v149, 0x3a800000, v158
	v_rsq_f32_e32 v149, v239
	s_nop 0
	v_mul_f32_e32 v252, 0xbfb8aa3b, v149
	v_pk_mul_f32 v[120:121], v[120:121], v[252:253] op_sel_hi:[1,0]
	v_pk_mul_f32 v[118:119], v[118:119], v[252:253] op_sel_hi:[1,0]
	v_pk_mul_f32 v[116:117], v[116:117], v[252:253] op_sel_hi:[1,0]
	v_pk_mul_f32 v[114:115], v[114:115], v[252:253] op_sel_hi:[1,0]
	v_exp_f32_e32 v118, v118
	v_exp_f32_e32 v119, v119
	v_exp_f32_e32 v120, v120
	v_exp_f32_e32 v121, v121
	v_exp_f32_e32 v114, v114
	v_exp_f32_e32 v115, v115
	v_exp_f32_e32 v116, v116
	v_exp_f32_e32 v117, v117
	v_fma_f32 v118, v118, v239, v239
	v_fma_f32 v119, v119, v239, v239
	v_fma_f32 v120, v120, v239, v239
	v_fma_f32 v121, v121, v239, v239
	v_fma_f32 v149, v114, v239, v239
	v_fma_f32 v159, v115, v239, v239
	v_fma_f32 v247, v116, v239, v239
	v_fma_f32 v252, v117, v239, v239
	v_rcp_f32_e32 v114, v118
	v_rcp_f32_e32 v115, v119
	v_rcp_f32_e32 v116, v120
	v_rcp_f32_e32 v117, v121
	v_rcp_f32_e32 v118, v149
	v_rcp_f32_e32 v119, v159
	v_rcp_f32_e32 v120, v247
	v_rcp_f32_e32 v121, v252
	v_pk_mul_f32 v[116:117], v[128:129], v[116:117]
	v_pk_mul_f32 v[114:115], v[126:127], v[114:115]
	v_pk_mul_f32 v[120:121], v[124:125], v[120:121]
	v_pk_mul_f32 v[118:119], v[244:245], v[118:119]
	v_cvt_pk_bf16_f32 v114, v114, v115
	v_cvt_pk_bf16_f32 v115, v116, v117
	v_cvt_pk_bf16_f32 v116, v118, v119
	v_cvt_pk_bf16_f32 v117, v120, v121
	global_store_dwordx4 v[248:249], v[114:117], off
	v_fmamk_f32 v239, v232, 0x3a800000, v158
	v_rsq_f32_e32 v121, v239
	s_nop 0
	v_mul_f32_e32 v120, 0xbfb8aa3b, v121
	v_pk_mul_f32 v[108:109], v[108:109], v[120:121] op_sel_hi:[1,0]
	v_pk_mul_f32 v[106:107], v[106:107], v[120:121] op_sel_hi:[1,0]
	v_pk_mul_f32 v[100:101], v[100:101], v[120:121] op_sel_hi:[1,0]
	v_pk_mul_f32 v[98:99], v[98:99], v[120:121] op_sel_hi:[1,0]
	v_exp_f32_e32 v106, v106
	v_exp_f32_e32 v107, v107
	v_exp_f32_e32 v108, v108
	v_exp_f32_e32 v109, v109
	v_exp_f32_e32 v98, v98
	v_exp_f32_e32 v99, v99
	v_exp_f32_e32 v100, v100
	v_exp_f32_e32 v101, v101
	v_fma_f32 v106, v106, v239, v239
	v_fma_f32 v107, v107, v239, v239
	v_fma_f32 v108, v108, v239, v239
	v_fma_f32 v109, v109, v239, v239
	v_fma_f32 v115, v98, v239, v239
	v_fma_f32 v120, v99, v239, v239
	v_fma_f32 v121, v100, v239, v239
	v_fma_f32 v125, v101, v239, v239
	v_rcp_f32_e32 v98, v106
	v_rcp_f32_e32 v99, v107
	v_rcp_f32_e32 v100, v108
	v_rcp_f32_e32 v101, v109
	v_rcp_f32_e32 v106, v115
	v_rcp_f32_e32 v107, v120
	v_rcp_f32_e32 v108, v121
	v_rcp_f32_e32 v109, v125
	v_pk_mul_f32 v[100:101], v[112:113], v[100:101]
	v_pk_mul_f32 v[98:99], v[110:111], v[98:99]
	v_pk_mul_f32 v[104:105], v[104:105], v[108:109]
	v_pk_mul_f32 v[102:103], v[102:103], v[106:107]
	s_mov_b32 s100, 0x16000
	v_lshl_add_u64 v[116:117], v[240:241], 0, s[100:101]
	v_cvt_pk_bf16_f32 v98, v98, v99
	v_cvt_pk_bf16_f32 v99, v100, v101
	v_cvt_pk_bf16_f32 v100, v102, v103
	v_cvt_pk_bf16_f32 v101, v104, v105
	global_store_dwordx4 v[116:117], v[98:101], off
	v_fmamk_f32 v239, v233, 0x3a800000, v158
	v_rsq_f32_e32 v105, v239
	s_nop 0
	v_mul_f32_e32 v104, 0xbfb8aa3b, v105
	v_pk_mul_f32 v[92:93], v[92:93], v[104:105] op_sel_hi:[1,0]
	v_pk_mul_f32 v[90:91], v[90:91], v[104:105] op_sel_hi:[1,0]
	v_pk_mul_f32 v[84:85], v[84:85], v[104:105] op_sel_hi:[1,0]
	v_pk_mul_f32 v[82:83], v[82:83], v[104:105] op_sel_hi:[1,0]
	v_exp_f32_e32 v90, v90
	v_exp_f32_e32 v91, v91
	v_exp_f32_e32 v92, v92
	v_exp_f32_e32 v93, v93
	v_exp_f32_e32 v82, v82
	v_exp_f32_e32 v83, v83
	v_exp_f32_e32 v84, v84
	v_exp_f32_e32 v85, v85
	v_fma_f32 v90, v90, v239, v239
	v_fma_f32 v91, v91, v239, v239
	v_fma_f32 v92, v92, v239, v239
	v_fma_f32 v93, v93, v239, v239
	v_fma_f32 v99, v82, v239, v239
	v_fma_f32 v104, v83, v239, v239
	v_fma_f32 v105, v84, v239, v239
	v_fma_f32 v107, v85, v239, v239
	v_rcp_f32_e32 v82, v90
	v_rcp_f32_e32 v83, v91
	v_rcp_f32_e32 v84, v92
	v_rcp_f32_e32 v85, v93
	v_rcp_f32_e32 v90, v99
	v_rcp_f32_e32 v91, v104
	v_rcp_f32_e32 v92, v105
	v_rcp_f32_e32 v93, v107
	v_pk_mul_f32 v[84:85], v[96:97], v[84:85]
	v_pk_mul_f32 v[82:83], v[94:95], v[82:83]
	v_pk_mul_f32 v[88:89], v[88:89], v[92:93]
	v_pk_mul_f32 v[86:87], v[86:87], v[90:91]
	s_mov_b32 s100, 0x2c000
	v_lshl_add_u64 v[100:101], v[240:241], 0, s[100:101]
	v_cvt_pk_bf16_f32 v82, v82, v83
	v_cvt_pk_bf16_f32 v83, v84, v85
	v_cvt_pk_bf16_f32 v84, v86, v87
	v_cvt_pk_bf16_f32 v85, v88, v89
	global_store_dwordx4 v[100:101], v[82:85], off
	s_nop 0
	s_nop 0
	s_mov_b32 s100, 0x42000
	v_lshl_add_u64 v[82:83], v[240:241], 0, s[100:101]
	v_fmamk_f32 v239, v234, 0x3a800000, v158
	v_rsq_f32_e32 v89, v239
	s_nop 0
	v_mul_f32_e32 v88, 0xbfb8aa3b, v89
	v_pk_mul_f32 v[76:77], v[76:77], v[88:89] op_sel_hi:[1,0]
	v_pk_mul_f32 v[74:75], v[74:75], v[88:89] op_sel_hi:[1,0]
	v_pk_mul_f32 v[68:69], v[68:69], v[88:89] op_sel_hi:[1,0]
	v_pk_mul_f32 v[66:67], v[66:67], v[88:89] op_sel_hi:[1,0]
	v_exp_f32_e32 v74, v74
	v_exp_f32_e32 v75, v75
	v_exp_f32_e32 v76, v76
	v_exp_f32_e32 v77, v77
	v_exp_f32_e32 v66, v66
	v_exp_f32_e32 v67, v67
	v_exp_f32_e32 v68, v68
	v_exp_f32_e32 v69, v69
	v_fma_f32 v74, v74, v239, v239
	v_fma_f32 v75, v75, v239, v239
	v_fma_f32 v76, v76, v239, v239
	v_fma_f32 v77, v77, v239, v239
	v_fma_f32 v85, v66, v239, v239
	v_fma_f32 v88, v67, v239, v239
	v_fma_f32 v89, v68, v239, v239
	v_fma_f32 v91, v69, v239, v239
	v_rcp_f32_e32 v66, v74
	v_rcp_f32_e32 v67, v75
	v_rcp_f32_e32 v68, v76
	v_rcp_f32_e32 v69, v77
	v_rcp_f32_e32 v74, v85
	v_rcp_f32_e32 v75, v88
	v_rcp_f32_e32 v76, v89
	v_rcp_f32_e32 v77, v91
	v_pk_mul_f32 v[68:69], v[80:81], v[68:69]
	v_pk_mul_f32 v[66:67], v[78:79], v[66:67]
	v_pk_mul_f32 v[72:73], v[72:73], v[76:77]
	v_pk_mul_f32 v[70:71], v[70:71], v[74:75]
	v_cvt_pk_bf16_f32 v66, v66, v67
	v_cvt_pk_bf16_f32 v67, v68, v69
	v_cvt_pk_bf16_f32 v68, v70, v71
	v_cvt_pk_bf16_f32 v69, v72, v73
	global_store_dwordx4 v[82:83], v[66:69], off
	v_fmamk_f32 v239, v235, 0x3a800000, v158
	v_rsq_f32_e32 v73, v239
	s_nop 0
	v_mul_f32_e32 v72, 0xbfb8aa3b, v73
	v_pk_mul_f32 v[60:61], v[60:61], v[72:73] op_sel_hi:[1,0]
	v_pk_mul_f32 v[58:59], v[58:59], v[72:73] op_sel_hi:[1,0]
	v_pk_mul_f32 v[52:53], v[52:53], v[72:73] op_sel_hi:[1,0]
	v_pk_mul_f32 v[50:51], v[50:51], v[72:73] op_sel_hi:[1,0]
	v_exp_f32_e32 v58, v58
	v_exp_f32_e32 v59, v59
	v_exp_f32_e32 v60, v60
	v_exp_f32_e32 v61, v61
	v_exp_f32_e32 v50, v50
	v_exp_f32_e32 v51, v51
	v_exp_f32_e32 v52, v52
	v_exp_f32_e32 v53, v53
	v_fma_f32 v58, v58, v239, v239
	v_fma_f32 v59, v59, v239, v239
	v_fma_f32 v60, v60, v239, v239
	v_fma_f32 v61, v61, v239, v239
	v_fma_f32 v67, v50, v239, v239
	v_fma_f32 v72, v51, v239, v239
	v_fma_f32 v73, v52, v239, v239
	v_fma_f32 v75, v53, v239, v239
	v_rcp_f32_e32 v50, v58
	v_rcp_f32_e32 v51, v59
	v_rcp_f32_e32 v52, v60
	v_rcp_f32_e32 v53, v61
	v_rcp_f32_e32 v58, v67
	v_rcp_f32_e32 v59, v72
	v_rcp_f32_e32 v60, v73
	v_rcp_f32_e32 v61, v75
	v_pk_mul_f32 v[52:53], v[64:65], v[52:53]
	v_pk_mul_f32 v[50:51], v[62:63], v[50:51]
	v_pk_mul_f32 v[56:57], v[56:57], v[60:61]
	v_pk_mul_f32 v[54:55], v[54:55], v[58:59]
	s_mov_b32 s100, 0xb0000
	v_lshl_add_u64 v[68:69], v[240:241], 0, s[100:101]
	v_cvt_pk_bf16_f32 v50, v50, v51
	v_cvt_pk_bf16_f32 v51, v52, v53
	v_cvt_pk_bf16_f32 v52, v54, v55
	v_cvt_pk_bf16_f32 v53, v56, v57
	global_store_dwordx4 v[68:69], v[50:53], off
	v_fmamk_f32 v239, v236, 0x3a800000, v158
	v_rsq_f32_e32 v57, v239
	s_nop 0
	v_mul_f32_e32 v56, 0xbfb8aa3b, v57
	v_pk_mul_f32 v[44:45], v[44:45], v[56:57] op_sel_hi:[1,0]
	v_pk_mul_f32 v[42:43], v[42:43], v[56:57] op_sel_hi:[1,0]
	v_pk_mul_f32 v[36:37], v[36:37], v[56:57] op_sel_hi:[1,0]
	v_pk_mul_f32 v[34:35], v[34:35], v[56:57] op_sel_hi:[1,0]
	v_exp_f32_e32 v42, v42
	v_exp_f32_e32 v43, v43
	v_exp_f32_e32 v44, v44
	v_exp_f32_e32 v45, v45
	v_exp_f32_e32 v34, v34
	v_exp_f32_e32 v35, v35
	v_exp_f32_e32 v36, v36
	v_exp_f32_e32 v37, v37
	v_fma_f32 v42, v42, v239, v239
	v_fma_f32 v43, v43, v239, v239
	v_fma_f32 v44, v44, v239, v239
	v_fma_f32 v45, v45, v239, v239
	v_fma_f32 v51, v34, v239, v239
	v_fma_f32 v56, v35, v239, v239
	v_fma_f32 v57, v36, v239, v239
	v_fma_f32 v59, v37, v239, v239
	v_rcp_f32_e32 v34, v42
	v_rcp_f32_e32 v35, v43
	v_rcp_f32_e32 v36, v44
	v_rcp_f32_e32 v37, v45
	v_rcp_f32_e32 v42, v51
	v_rcp_f32_e32 v43, v56
	v_rcp_f32_e32 v44, v57
	v_rcp_f32_e32 v45, v59
	v_pk_mul_f32 v[36:37], v[48:49], v[36:37]
	v_pk_mul_f32 v[34:35], v[46:47], v[34:35]
	v_pk_mul_f32 v[40:41], v[40:41], v[44:45]
	v_pk_mul_f32 v[38:39], v[38:39], v[42:43]
	s_mov_b32 s100, 0xc6000
	v_lshl_add_u64 v[52:53], v[240:241], 0, s[100:101]
	v_cvt_pk_bf16_f32 v34, v34, v35
	v_cvt_pk_bf16_f32 v35, v36, v37
	v_cvt_pk_bf16_f32 v36, v38, v39
	v_cvt_pk_bf16_f32 v37, v40, v41
	global_store_dwordx4 v[52:53], v[34:37], off
	v_fmamk_f32 v239, v237, 0x3a800000, v158
	v_rsq_f32_e32 v41, v239
	s_nop 0
	v_mul_f32_e32 v40, 0xbfb8aa3b, v41
	v_pk_mul_f32 v[28:29], v[28:29], v[40:41] op_sel_hi:[1,0]
	v_pk_mul_f32 v[26:27], v[26:27], v[40:41] op_sel_hi:[1,0]
	v_pk_mul_f32 v[20:21], v[20:21], v[40:41] op_sel_hi:[1,0]
	v_pk_mul_f32 v[18:19], v[18:19], v[40:41] op_sel_hi:[1,0]
	v_exp_f32_e32 v26, v26
	v_exp_f32_e32 v27, v27
	v_exp_f32_e32 v28, v28
	v_exp_f32_e32 v29, v29
	v_exp_f32_e32 v18, v18
	v_exp_f32_e32 v19, v19
	v_exp_f32_e32 v20, v20
	v_exp_f32_e32 v21, v21
	v_fma_f32 v26, v26, v239, v239
	v_fma_f32 v27, v27, v239, v239
	v_fma_f32 v28, v28, v239, v239
	v_fma_f32 v29, v29, v239, v239
	v_fma_f32 v35, v18, v239, v239
	v_fma_f32 v40, v19, v239, v239
	v_fma_f32 v41, v20, v239, v239
	v_fma_f32 v43, v21, v239, v239
	v_rcp_f32_e32 v18, v26
	v_rcp_f32_e32 v19, v27
	v_rcp_f32_e32 v20, v28
	v_rcp_f32_e32 v21, v29
	v_rcp_f32_e32 v26, v35
	v_rcp_f32_e32 v27, v40
	v_rcp_f32_e32 v28, v41
	v_rcp_f32_e32 v29, v43
	v_pk_mul_f32 v[20:21], v[32:33], v[20:21]
	v_pk_mul_f32 v[18:19], v[30:31], v[18:19]
	v_pk_mul_f32 v[24:25], v[24:25], v[28:29]
	v_pk_mul_f32 v[22:23], v[22:23], v[26:27]
	s_mov_b32 s100, 0xdc000
	v_lshl_add_u64 v[36:37], v[240:241], 0, s[100:101]
	v_cvt_pk_bf16_f32 v18, v18, v19
	v_cvt_pk_bf16_f32 v19, v20, v21
	v_cvt_pk_bf16_f32 v20, v22, v23
	v_cvt_pk_bf16_f32 v21, v24, v25
	global_store_dwordx4 v[36:37], v[18:21], off
	s_nop 0
	s_nop 0
	v_fmamk_f32 v239, v238, 0x3a800000, v158
	v_rsq_f32_e32 v21, v239
	s_nop 0
	v_mul_f32_e32 v20, 0xbfb8aa3b, v21
	v_pk_mul_f32 v[12:13], v[12:13], v[20:21] op_sel_hi:[1,0]
	v_pk_mul_f32 v[10:11], v[10:11], v[20:21] op_sel_hi:[1,0]
	v_pk_mul_f32 v[8:9], v[8:9], v[20:21] op_sel_hi:[1,0]
	v_pk_mul_f32 v[6:7], v[6:7], v[20:21] op_sel_hi:[1,0]
	v_exp_f32_e32 v10, v10
	v_exp_f32_e32 v11, v11
	v_exp_f32_e32 v12, v12
	v_exp_f32_e32 v13, v13
	v_exp_f32_e32 v6, v6
	v_exp_f32_e32 v7, v7
	v_exp_f32_e32 v8, v8
	v_exp_f32_e32 v9, v9
	v_fma_f32 v10, v10, v239, v239
	v_fma_f32 v11, v11, v239, v239
	v_fma_f32 v12, v12, v239, v239
	v_fma_f32 v13, v13, v239, v239
	v_fma_f32 v20, v6, v239, v239
	v_fma_f32 v21, v7, v239, v239
	v_fma_f32 v23, v8, v239, v239
	v_fma_f32 v24, v9, v239, v239
	v_rcp_f32_e32 v6, v10
	v_rcp_f32_e32 v7, v11
	v_rcp_f32_e32 v8, v12
	v_rcp_f32_e32 v9, v13
	v_rcp_f32_e32 v10, v20
	v_rcp_f32_e32 v11, v21
	v_rcp_f32_e32 v12, v23
	v_rcp_f32_e32 v13, v24
	v_pk_mul_f32 v[8:9], v[16:17], v[8:9]
	v_pk_mul_f32 v[6:7], v[14:15], v[6:7]
	v_pk_mul_f32 v[12:13], v[4:5], v[12:13]
	v_pk_mul_f32 v[4:5], v[2:3], v[10:11]
	s_mov_b32 s100, 0xf2000
	v_lshl_add_u64 v[18:19], v[240:241], 0, s[100:101]
	v_cvt_pk_bf16_f32 v2, v6, v7
	v_cvt_pk_bf16_f32 v3, v8, v9
	v_cvt_pk_bf16_f32 v4, v4, v5
	v_cvt_pk_bf16_f32 v5, v12, v13
	s_mov_b64 s[4:5], -1
	global_store_dwordx4 v[18:19], v[2:5], off
	s_cbranch_vccnz .LBB0_836
	s_andn2_b64 vcc, exec, s[8:9]
	s_cbranch_vccnz .LBB0_835
	s_barrier
	s_branch .LBB0_835

.Lz_post_p8b:
	s_lshl_b32 s25, s46, 8
	v_add_u32_e32 v148, s25, v150
	v_ashrrev_i32_e32 v149, 31, v148
	v_lshl_add_u64 v[244:245], v[148:149], 2, s[8:9]
	global_load_dword v149, v[244:245], off
	global_load_dword v232, v[244:245], off offset:64
	global_load_dword v233, v[244:245], off offset:128
	global_load_dword v234, v[244:245], off offset:192
	global_load_dword v235, v[244:245], off offset:512
	global_load_dword v236, v[244:245], off offset:576
	global_load_dword v237, v[244:245], off offset:640
	global_load_dword v238, v[244:245], off offset:704
	v_pk_mul_f32 v[128:129], v[120:121], v[128:129]
	v_pk_mul_f32 v[126:127], v[118:119], v[126:127]
	v_pk_mul_f32 v[124:125], v[116:117], v[124:125]
	v_pk_mul_f32 v[244:245], v[114:115], v[122:123]
	s_lshl_b32 s46, s47, 7
	v_mov_b64_e32 v[122:123], s[10:11]
	s_ashr_i32 s47, s46, 31
	v_mad_i64_i32 v[248:249], s[48:49], v148, s68, v[122:123]
	s_lshl_b64 s[46:47], s[46:47], 1
	v_lshl_add_u64 v[248:249], v[248:249], 0, s[46:47]
	v_lshl_add_u64 v[248:249], v[248:249], 0, v[138:139]
	v_mov_b64_e32 v[240:241], v[248:249]
	s_mov_b32 s101, 0
	v_pk_mul_f32 v[112:113], v[108:109], v[112:113]
	v_pk_mul_f32 v[110:111], v[106:107], v[110:111]
	v_pk_mul_f32 v[104:105], v[100:101], v[104:105]
	v_pk_mul_f32 v[102:103], v[98:99], v[102:103]
	v_pk_mul_f32 v[96:97], v[92:93], v[96:97]
	v_pk_mul_f32 v[94:95], v[90:91], v[94:95]
	v_pk_mul_f32 v[88:89], v[84:85], v[88:89]
	v_pk_mul_f32 v[86:87], v[82:83], v[86:87]
	v_pk_mul_f32 v[80:81], v[76:77], v[80:81]
	v_pk_mul_f32 v[78:79], v[74:75], v[78:79]
	v_pk_mul_f32 v[72:73], v[68:69], v[72:73]
	v_pk_mul_f32 v[70:71], v[66:67], v[70:71]
	v_pk_mul_f32 v[64:65], v[60:61], v[64:65]
	v_pk_mul_f32 v[62:63], v[58:59], v[62:63]
	v_pk_mul_f32 v[56:57], v[52:53], v[56:57]
	v_pk_mul_f32 v[54:55], v[50:51], v[54:55]
	v_pk_mul_f32 v[48:49], v[44:45], v[48:49]
	v_pk_mul_f32 v[46:47], v[42:43], v[46:47]
	v_pk_mul_f32 v[40:41], v[36:37], v[40:41]
	v_pk_mul_f32 v[38:39], v[34:35], v[38:39]
	v_pk_mul_f32 v[32:33], v[28:29], v[32:33]
	v_pk_mul_f32 v[30:31], v[26:27], v[30:31]
	v_pk_mul_f32 v[24:25], v[20:21], v[24:25]
	v_pk_mul_f32 v[22:23], v[18:19], v[22:23]
	v_pk_mul_f32 v[16:17], v[12:13], v[16:17]
	v_pk_mul_f32 v[14:15], v[10:11], v[14:15]
	v_pk_mul_f32 v[4:5], v[8:9], v[4:5]
	v_pk_mul_f32 v[2:3], v[6:7], v[2:3]
	s_and_b64 vcc, exec, s[16:17]
	s_cbranch_vccz .LBB0_1133
	s_barrier
.LBB0_1133:
	ds_read_b128 v[160:163], v155
	ds_read_b128 v[164:167], v155 offset:1024
	ds_read_b128 v[168:171], v155 offset:2048
	ds_read_b128 v[172:175], v155 offset:3072
	ds_read_b128 v[176:179], v156
	ds_read_b128 v[180:183], v156 offset:1024
	ds_read_b128 v[184:187], v156 offset:2048
	ds_read_b128 v[188:191], v156 offset:3072
	ds_read_b128 v[192:195], v157
	ds_read_b128 v[196:199], v157 offset:1024
	ds_read_b128 v[200:203], v157 offset:2048
	ds_read_b128 v[204:207], v157 offset:3072
	ds_read_b128 v[208:211], v157 offset:4096
	ds_read_b128 v[212:215], v157 offset:5120
	ds_read_b128 v[216:219], v157 offset:6144
	ds_read_b128 v[220:223], v157 offset:7168
	s_andn2_b64 vcc, exec, s[4:5]
	s_waitcnt vmcnt(0)
	v_fmamk_f32 v239, v149, 0x3a800000, v158
	v_rsq_f32_e32 v149, v239
	s_nop 0
	v_mul_f32_e32 v252, 0xbfb8aa3b, v149
	v_pk_mul_f32 v[120:121], v[120:121], v[252:253] op_sel_hi:[1,0]
	v_pk_mul_f32 v[118:119], v[118:119], v[252:253] op_sel_hi:[1,0]
	v_pk_mul_f32 v[116:117], v[116:117], v[252:253] op_sel_hi:[1,0]
	v_pk_mul_f32 v[114:115], v[114:115], v[252:253] op_sel_hi:[1,0]
	v_exp_f32_e32 v118, v118
	v_exp_f32_e32 v119, v119
	v_exp_f32_e32 v120, v120
	v_exp_f32_e32 v121, v121
	v_exp_f32_e32 v114, v114
	v_exp_f32_e32 v115, v115
	v_exp_f32_e32 v116, v116
	v_exp_f32_e32 v117, v117
	v_fma_f32 v118, v118, v239, v239
	v_fma_f32 v119, v119, v239, v239
	v_fma_f32 v120, v120, v239, v239
	v_fma_f32 v121, v121, v239, v239
	v_fma_f32 v149, v114, v239, v239
	v_fma_f32 v159, v115, v239, v239
	v_fma_f32 v247, v116, v239, v239
	v_fma_f32 v252, v117, v239, v239
	v_rcp_f32_e32 v114, v118
	v_rcp_f32_e32 v115, v119
	v_rcp_f32_e32 v116, v120
	v_rcp_f32_e32 v117, v121
	v_rcp_f32_e32 v118, v149
	v_rcp_f32_e32 v119, v159
	v_rcp_f32_e32 v120, v247
	v_rcp_f32_e32 v121, v252
	v_pk_mul_f32 v[116:117], v[128:129], v[116:117]
	v_pk_mul_f32 v[114:115], v[126:127], v[114:115]
	v_pk_mul_f32 v[120:121], v[124:125], v[120:121]
	v_pk_mul_f32 v[118:119], v[244:245], v[118:119]
	v_cvt_pk_bf16_f32 v114, v114, v115
	v_cvt_pk_bf16_f32 v115, v116, v117
	v_cvt_pk_bf16_f32 v116, v118, v119
	v_cvt_pk_bf16_f32 v117, v120, v121
	global_store_dwordx4 v[248:249], v[114:117], off
	v_fmamk_f32 v239, v232, 0x3a800000, v158
	v_rsq_f32_e32 v121, v239
	s_nop 0
	v_mul_f32_e32 v120, 0xbfb8aa3b, v121
	v_pk_mul_f32 v[108:109], v[108:109], v[120:121] op_sel_hi:[1,0]
	v_pk_mul_f32 v[106:107], v[106:107], v[120:121] op_sel_hi:[1,0]
	v_pk_mul_f32 v[100:101], v[100:101], v[120:121] op_sel_hi:[1,0]
	v_pk_mul_f32 v[98:99], v[98:99], v[120:121] op_sel_hi:[1,0]
	v_exp_f32_e32 v106, v106
	v_exp_f32_e32 v107, v107
	v_exp_f32_e32 v108, v108
	v_exp_f32_e32 v109, v109
	v_exp_f32_e32 v98, v98
	v_exp_f32_e32 v99, v99
	v_exp_f32_e32 v100, v100
	v_exp_f32_e32 v101, v101
	v_fma_f32 v106, v106, v239, v239
	v_fma_f32 v107, v107, v239, v239
	v_fma_f32 v108, v108, v239, v239
	v_fma_f32 v109, v109, v239, v239
	v_fma_f32 v115, v98, v239, v239
	v_fma_f32 v120, v99, v239, v239
	v_fma_f32 v121, v100, v239, v239
	v_fma_f32 v125, v101, v239, v239
	v_rcp_f32_e32 v98, v106
	v_rcp_f32_e32 v99, v107
	v_rcp_f32_e32 v100, v108
	v_rcp_f32_e32 v101, v109
	v_rcp_f32_e32 v106, v115
	v_rcp_f32_e32 v107, v120
	v_rcp_f32_e32 v108, v121
	v_rcp_f32_e32 v109, v125
	v_pk_mul_f32 v[100:101], v[112:113], v[100:101]
	v_pk_mul_f32 v[98:99], v[110:111], v[98:99]
	v_pk_mul_f32 v[104:105], v[104:105], v[108:109]
	v_pk_mul_f32 v[102:103], v[102:103], v[106:107]
	s_mov_b32 s100, 0x16000
	v_lshl_add_u64 v[116:117], v[240:241], 0, s[100:101]
	v_cvt_pk_bf16_f32 v98, v98, v99
	v_cvt_pk_bf16_f32 v99, v100, v101
	v_cvt_pk_bf16_f32 v100, v102, v103
	v_cvt_pk_bf16_f32 v101, v104, v105
	global_store_dwordx4 v[116:117], v[98:101], off
	v_fmamk_f32 v239, v233, 0x3a800000, v158
	v_rsq_f32_e32 v105, v239
	s_nop 0
	v_mul_f32_e32 v104, 0xbfb8aa3b, v105
	v_pk_mul_f32 v[92:93], v[92:93], v[104:105] op_sel_hi:[1,0]
	v_pk_mul_f32 v[90:91], v[90:91], v[104:105] op_sel_hi:[1,0]
	v_pk_mul_f32 v[84:85], v[84:85], v[104:105] op_sel_hi:[1,0]
	v_pk_mul_f32 v[82:83], v[82:83], v[104:105] op_sel_hi:[1,0]
	v_exp_f32_e32 v90, v90
	v_exp_f32_e32 v91, v91
	v_exp_f32_e32 v92, v92
	v_exp_f32_e32 v93, v93
	v_exp_f32_e32 v82, v82
	v_exp_f32_e32 v83, v83
	v_exp_f32_e32 v84, v84
	v_exp_f32_e32 v85, v85
	v_fma_f32 v90, v90, v239, v239
	v_fma_f32 v91, v91, v239, v239
	v_fma_f32 v92, v92, v239, v239
	v_fma_f32 v93, v93, v239, v239
	v_fma_f32 v99, v82, v239, v239
	v_fma_f32 v104, v83, v239, v239
	v_fma_f32 v105, v84, v239, v239
	v_fma_f32 v107, v85, v239, v239
	v_rcp_f32_e32 v82, v90
	v_rcp_f32_e32 v83, v91
	v_rcp_f32_e32 v84, v92
	v_rcp_f32_e32 v85, v93
	v_rcp_f32_e32 v90, v99
	v_rcp_f32_e32 v91, v104
	v_rcp_f32_e32 v92, v105
	v_rcp_f32_e32 v93, v107
	v_pk_mul_f32 v[84:85], v[96:97], v[84:85]
	v_pk_mul_f32 v[82:83], v[94:95], v[82:83]
	v_pk_mul_f32 v[88:89], v[88:89], v[92:93]
	v_pk_mul_f32 v[86:87], v[86:87], v[90:91]
	s_mov_b32 s100, 0x2c000
	v_lshl_add_u64 v[100:101], v[240:241], 0, s[100:101]
	v_cvt_pk_bf16_f32 v82, v82, v83
	v_cvt_pk_bf16_f32 v83, v84, v85
	v_cvt_pk_bf16_f32 v84, v86, v87
	v_cvt_pk_bf16_f32 v85, v88, v89
	global_store_dwordx4 v[100:101], v[82:85], off
	s_nop 0
	s_nop 0
	s_mov_b32 s100, 0x42000
	v_lshl_add_u64 v[82:83], v[240:241], 0, s[100:101]
	v_fmamk_f32 v239, v234, 0x3a800000, v158
	v_rsq_f32_e32 v89, v239
	s_nop 0
	v_mul_f32_e32 v88, 0xbfb8aa3b, v89
	v_pk_mul_f32 v[76:77], v[76:77], v[88:89] op_sel_hi:[1,0]
	v_pk_mul_f32 v[74:75], v[74:75], v[88:89] op_sel_hi:[1,0]
	v_pk_mul_f32 v[68:69], v[68:69], v[88:89] op_sel_hi:[1,0]
	v_pk_mul_f32 v[66:67], v[66:67], v[88:89] op_sel_hi:[1,0]
	v_exp_f32_e32 v74, v74
	v_exp_f32_e32 v75, v75
	v_exp_f32_e32 v76, v76
	v_exp_f32_e32 v77, v77
	v_exp_f32_e32 v66, v66
	v_exp_f32_e32 v67, v67
	v_exp_f32_e32 v68, v68
	v_exp_f32_e32 v69, v69
	v_fma_f32 v74, v74, v239, v239
	v_fma_f32 v75, v75, v239, v239
	v_fma_f32 v76, v76, v239, v239
	v_fma_f32 v77, v77, v239, v239
	v_fma_f32 v85, v66, v239, v239
	v_fma_f32 v88, v67, v239, v239
	v_fma_f32 v89, v68, v239, v239
	v_fma_f32 v91, v69, v239, v239
	v_rcp_f32_e32 v66, v74
	v_rcp_f32_e32 v67, v75
	v_rcp_f32_e32 v68, v76
	v_rcp_f32_e32 v69, v77
	v_rcp_f32_e32 v74, v85
	v_rcp_f32_e32 v75, v88
	v_rcp_f32_e32 v76, v89
	v_rcp_f32_e32 v77, v91
	v_pk_mul_f32 v[68:69], v[80:81], v[68:69]
	v_pk_mul_f32 v[66:67], v[78:79], v[66:67]
	v_pk_mul_f32 v[72:73], v[72:73], v[76:77]
	v_pk_mul_f32 v[70:71], v[70:71], v[74:75]
	v_cvt_pk_bf16_f32 v66, v66, v67
	v_cvt_pk_bf16_f32 v67, v68, v69
	v_cvt_pk_bf16_f32 v68, v70, v71
	v_cvt_pk_bf16_f32 v69, v72, v73
	global_store_dwordx4 v[82:83], v[66:69], off
	v_fmamk_f32 v239, v235, 0x3a800000, v158
	v_rsq_f32_e32 v73, v239
	s_nop 0
	v_mul_f32_e32 v72, 0xbfb8aa3b, v73
	v_pk_mul_f32 v[60:61], v[60:61], v[72:73] op_sel_hi:[1,0]
	v_pk_mul_f32 v[58:59], v[58:59], v[72:73] op_sel_hi:[1,0]
	v_pk_mul_f32 v[52:53], v[52:53], v[72:73] op_sel_hi:[1,0]
	v_pk_mul_f32 v[50:51], v[50:51], v[72:73] op_sel_hi:[1,0]
	v_exp_f32_e32 v58, v58
	v_exp_f32_e32 v59, v59
	v_exp_f32_e32 v60, v60
	v_exp_f32_e32 v61, v61
	v_exp_f32_e32 v50, v50
	v_exp_f32_e32 v51, v51
	v_exp_f32_e32 v52, v52
	v_exp_f32_e32 v53, v53
	v_fma_f32 v58, v58, v239, v239
	v_fma_f32 v59, v59, v239, v239
	v_fma_f32 v60, v60, v239, v239
	v_fma_f32 v61, v61, v239, v239
	v_fma_f32 v67, v50, v239, v239
	v_fma_f32 v72, v51, v239, v239
	v_fma_f32 v73, v52, v239, v239
	v_fma_f32 v75, v53, v239, v239
	v_rcp_f32_e32 v50, v58
	v_rcp_f32_e32 v51, v59
	v_rcp_f32_e32 v52, v60
	v_rcp_f32_e32 v53, v61
	v_rcp_f32_e32 v58, v67
	v_rcp_f32_e32 v59, v72
	v_rcp_f32_e32 v60, v73
	v_rcp_f32_e32 v61, v75
	v_pk_mul_f32 v[52:53], v[64:65], v[52:53]
	v_pk_mul_f32 v[50:51], v[62:63], v[50:51]
	v_pk_mul_f32 v[56:57], v[56:57], v[60:61]
	v_pk_mul_f32 v[54:55], v[54:55], v[58:59]
	s_mov_b32 s100, 0xb0000
	v_lshl_add_u64 v[68:69], v[240:241], 0, s[100:101]
	v_cvt_pk_bf16_f32 v50, v50, v51
	v_cvt_pk_bf16_f32 v51, v52, v53
	v_cvt_pk_bf16_f32 v52, v54, v55
	v_cvt_pk_bf16_f32 v53, v56, v57
	global_store_dwordx4 v[68:69], v[50:53], off
	v_fmamk_f32 v239, v236, 0x3a800000, v158
	v_rsq_f32_e32 v57, v239
	s_nop 0
	v_mul_f32_e32 v56, 0xbfb8aa3b, v57
	v_pk_mul_f32 v[44:45], v[44:45], v[56:57] op_sel_hi:[1,0]
	v_pk_mul_f32 v[42:43], v[42:43], v[56:57] op_sel_hi:[1,0]
	v_pk_mul_f32 v[36:37], v[36:37], v[56:57] op_sel_hi:[1,0]
	v_pk_mul_f32 v[34:35], v[34:35], v[56:57] op_sel_hi:[1,0]
	v_exp_f32_e32 v42, v42
	v_exp_f32_e32 v43, v43
	v_exp_f32_e32 v44, v44
	v_exp_f32_e32 v45, v45
	v_exp_f32_e32 v34, v34
	v_exp_f32_e32 v35, v35
	v_exp_f32_e32 v36, v36
	v_exp_f32_e32 v37, v37
	v_fma_f32 v42, v42, v239, v239
	v_fma_f32 v43, v43, v239, v239
	v_fma_f32 v44, v44, v239, v239
	v_fma_f32 v45, v45, v239, v239
	v_fma_f32 v51, v34, v239, v239
	v_fma_f32 v56, v35, v239, v239
	v_fma_f32 v57, v36, v239, v239
	v_fma_f32 v59, v37, v239, v239
	v_rcp_f32_e32 v34, v42
	v_rcp_f32_e32 v35, v43
	v_rcp_f32_e32 v36, v44
	v_rcp_f32_e32 v37, v45
	v_rcp_f32_e32 v42, v51
	v_rcp_f32_e32 v43, v56
	v_rcp_f32_e32 v44, v57
	v_rcp_f32_e32 v45, v59
	v_pk_mul_f32 v[36:37], v[48:49], v[36:37]
	v_pk_mul_f32 v[34:35], v[46:47], v[34:35]
	v_pk_mul_f32 v[40:41], v[40:41], v[44:45]
	v_pk_mul_f32 v[38:39], v[38:39], v[42:43]
	s_mov_b32 s100, 0xc6000
	v_lshl_add_u64 v[52:53], v[240:241], 0, s[100:101]
	v_cvt_pk_bf16_f32 v34, v34, v35
	v_cvt_pk_bf16_f32 v35, v36, v37
	v_cvt_pk_bf16_f32 v36, v38, v39
	v_cvt_pk_bf16_f32 v37, v40, v41
	global_store_dwordx4 v[52:53], v[34:37], off
	v_fmamk_f32 v239, v237, 0x3a800000, v158
	v_rsq_f32_e32 v41, v239
	s_nop 0
	v_mul_f32_e32 v40, 0xbfb8aa3b, v41
	v_pk_mul_f32 v[28:29], v[28:29], v[40:41] op_sel_hi:[1,0]
	v_pk_mul_f32 v[26:27], v[26:27], v[40:41] op_sel_hi:[1,0]
	v_pk_mul_f32 v[20:21], v[20:21], v[40:41] op_sel_hi:[1,0]
	v_pk_mul_f32 v[18:19], v[18:19], v[40:41] op_sel_hi:[1,0]
	v_exp_f32_e32 v26, v26
	v_exp_f32_e32 v27, v27
	v_exp_f32_e32 v28, v28
	v_exp_f32_e32 v29, v29
	v_exp_f32_e32 v18, v18
	v_exp_f32_e32 v19, v19
	v_exp_f32_e32 v20, v20
	v_exp_f32_e32 v21, v21
	v_fma_f32 v26, v26, v239, v239
	v_fma_f32 v27, v27, v239, v239
	v_fma_f32 v28, v28, v239, v239
	v_fma_f32 v29, v29, v239, v239
	v_fma_f32 v35, v18, v239, v239
	v_fma_f32 v40, v19, v239, v239
	v_fma_f32 v41, v20, v239, v239
	v_fma_f32 v43, v21, v239, v239
	v_rcp_f32_e32 v18, v26
	v_rcp_f32_e32 v19, v27
	v_rcp_f32_e32 v20, v28
	v_rcp_f32_e32 v21, v29
	v_rcp_f32_e32 v26, v35
	v_rcp_f32_e32 v27, v40
	v_rcp_f32_e32 v28, v41
	v_rcp_f32_e32 v29, v43
	v_pk_mul_f32 v[20:21], v[32:33], v[20:21]
	v_pk_mul_f32 v[18:19], v[30:31], v[18:19]
	v_pk_mul_f32 v[24:25], v[24:25], v[28:29]
	v_pk_mul_f32 v[22:23], v[22:23], v[26:27]
	s_mov_b32 s100, 0xdc000
	v_lshl_add_u64 v[36:37], v[240:241], 0, s[100:101]
	v_cvt_pk_bf16_f32 v18, v18, v19
	v_cvt_pk_bf16_f32 v19, v20, v21
	v_cvt_pk_bf16_f32 v20, v22, v23
	v_cvt_pk_bf16_f32 v21, v24, v25
	global_store_dwordx4 v[36:37], v[18:21], off
	s_nop 0
	s_nop 0
	v_fmamk_f32 v239, v238, 0x3a800000, v158
	v_rsq_f32_e32 v21, v239
	s_nop 0
	v_mul_f32_e32 v20, 0xbfb8aa3b, v21
	v_pk_mul_f32 v[12:13], v[12:13], v[20:21] op_sel_hi:[1,0]
	v_pk_mul_f32 v[10:11], v[10:11], v[20:21] op_sel_hi:[1,0]
	v_pk_mul_f32 v[8:9], v[8:9], v[20:21] op_sel_hi:[1,0]
	v_pk_mul_f32 v[6:7], v[6:7], v[20:21] op_sel_hi:[1,0]
	v_exp_f32_e32 v10, v10
	v_exp_f32_e32 v11, v11
	v_exp_f32_e32 v12, v12
	v_exp_f32_e32 v13, v13
	v_exp_f32_e32 v6, v6
	v_exp_f32_e32 v7, v7
	v_exp_f32_e32 v8, v8
	v_exp_f32_e32 v9, v9
	v_fma_f32 v10, v10, v239, v239
	v_fma_f32 v11, v11, v239, v239
	v_fma_f32 v12, v12, v239, v239
	v_fma_f32 v13, v13, v239, v239
	v_fma_f32 v20, v6, v239, v239
	v_fma_f32 v21, v7, v239, v239
	v_fma_f32 v23, v8, v239, v239
	v_fma_f32 v24, v9, v239, v239
	v_rcp_f32_e32 v6, v10
	v_rcp_f32_e32 v7, v11
	v_rcp_f32_e32 v8, v12
	v_rcp_f32_e32 v9, v13
	v_rcp_f32_e32 v10, v20
	v_rcp_f32_e32 v11, v21
	v_rcp_f32_e32 v12, v23
	v_rcp_f32_e32 v13, v24
	v_pk_mul_f32 v[8:9], v[16:17], v[8:9]
	v_pk_mul_f32 v[6:7], v[14:15], v[6:7]
	v_pk_mul_f32 v[12:13], v[4:5], v[12:13]
	v_pk_mul_f32 v[4:5], v[2:3], v[10:11]
	s_mov_b32 s100, 0xf2000
	v_lshl_add_u64 v[18:19], v[240:241], 0, s[100:101]
	v_cvt_pk_bf16_f32 v2, v6, v7
	v_cvt_pk_bf16_f32 v3, v8, v9
	v_cvt_pk_bf16_f32 v4, v4, v5
	v_cvt_pk_bf16_f32 v5, v12, v13
	s_mov_b64 s[4:5], -1
	global_store_dwordx4 v[18:19], v[2:5], off
	s_cbranch_vccnz .LBB0_1126
	s_andn2_b64 vcc, exec, s[6:7]
	s_cbranch_vccnz .LBB0_1125
	s_barrier
	s_branch .LBB0_1125
